# v65 + phase 7 units dealt by blockIdx (20 busy workgroups per XCD instead of 24/16)
# speedup vs baseline: 1.0035x; 1.0005x over previous
;     DI bool next(int i, Unit& u) const {
;         const int n = n0 + n1 + n2, R = n / G, r = n - R * G; const bool split = false && (2 * r == G) && ((G & 15) == 0);
;         long L = (long)i * G + c; int half = 0;
;         if (split && i >= R) { if (i > R) return false; const int xcd = c & 7, idx = c >> 3; L = (long)R * G + (idx >> 1) * 8 + xcd; half = 1 + (idx & 1); }
;         u.half = half;
;         if (L < n0) { map(s0, (int)L, u); if (half == 2) u.A += s0.aHalf; return true; } L -= n0;
.LBB0_861:
	s_cmp_lt_i32 s34, 8
	s_cselect_b64 s[4:5], -1, 0
	s_and_b64 s[8:9], s[4:5], s[2:3]
	s_andn2_b64 vcc, exec, s[8:9]
	s_cbranch_vccnz .LBB0_898
	s_mov_b64 s[2:3], s[0:1]
	s_load_dwordx2 s[10:11], s[2:3], 0xa8
	v_mbcnt_hi_u32_b32 v8, -1, v254
	v_mov_b32_e32 v9, v8
	s_waitcnt lgkmcnt(0)
	s_add_u32 s42, s10, 0xad00000
	s_addc_u32 s43, s11, 0
	s_add_u32 s44, s10, 0x5700000
	s_addc_u32 s45, s11, 0
	s_lshl_b32 s2, s6, 3
	s_lshr_b32 s3, s6, 5
	s_and_b32 s2, s2, 0xf8
	s_or_b32 s2, s2, s3
	s_cmpk_eq_i32 s7, 0x100
	s_mov_b32 s46, s6
	s_cmpk_lt_i32 s46, 0xa0
	s_cselect_b64 s[2:3], -1, 0
	s_cmpk_gt_i32 s46, 0x9f
	s_cbranch_scc1 .LBB0_864
	s_ashr_i32 s4, s46, 31
	s_lshr_b32 s4, s4, 29
	s_add_i32 s4, s46, s4
	s_ashr_i32 s5, s4, 3
	s_and_b32 s4, s4, -8
	s_sub_i32 s4, s46, s4
	s_cmp_lt_i32 s4, 0
	s_cselect_b32 s12, 21, 20
	s_mul_i32 s4, s4, s12
	s_add_i32 s4, s4, s5
	s_mul_hi_i32 s5, s4, 0x66666667
	s_lshr_b32 s12, s5, 31
	s_ashr_i32 s5, s5, 3
	s_add_i32 s5, s5, s12
	s_lshl_b32 s12, s5, 2
	s_mul_i32 s5, s5, 20
	s_sub_i32 s5, s4, s5
	s_bfe_i32 s4, s5, 0x80000
	s_bfe_u32 s4, s4, 0x2000d
	s_add_i32 s13, s5, s4
	s_bfe_i32 s4, s13, 0x80000
	s_and_b32 s13, s13, 0xfc
	s_sub_i32 s5, s5, s13
	s_sext_i32_i8 s5, s5
	s_add_i32 s26, s12, s5
	s_sext_i32_i16 s14, s4
	s_ashr_i32 s27, s26, 31
	s_lshr_b32 s4, s14, 2
	s_ashr_i32 s63, s14, 2
	s_lshl_b64 s[12:13], s[26:27], 20
	s_add_u32 s36, s42, s12
	s_addc_u32 s37, s43, s13
	s_bfe_i64 s[4:5], s[4:5], 0x100000
	s_lshl_b64 s[4:5], s[4:5], 20
	s_add_u32 s38, s44, s4
	s_addc_u32 s39, s45, s5
	s_andn2_b64 vcc, exec, s[2:3]
	s_cbranch_vccz .LBB0_865
	s_branch .LBB0_898

; DI void phase0(CP& p, LAS unsigned char* lds, int wid) {
;     ...
;     for (int it0 = gw; it0 < NCONV + NXROW; it0 += nw) {
;         const int it = it0 < NCONV ? NCONV - 1 - it0 : it0;
;         if (it < NCONV) {
;             const float* src; const float* src2 = nullptr; const float* gain = nullptr; bf16_t* dst; int ld, K, mode = CM_ID, coff = 0, t0;
;             if (it < 256) { src = p.w_in_ab; gain = p.g_mix; dst = WSB(OFF_W1UZ); ld = 3072; K = 2048; mode = CM_UZ; t0 = 0; }
;             else if (it < 384) { src = p.w_in_ab; gain = p.g_mix; dst = WSB(OFF_W1V); ld = 3072; K = 2048; coff = 1024; t0 = 256; }
;             else if (it < 640) { src = p.w_out_ab; dst = WSB(OFF_WOAB); ld = 2048; K = 2048; mode = CM_P32; t0 = 384; }
;             else if (it < 2048) { src = p.w_gate; src2 = p.w_up; gain = p.g_ffn; dst = WSB(OFF_WGU0); ld = DFF; K = 2048; mode = CM_GU; t0 = 640; }
;             else if (it < 2752) { src = p.w_down; dst = WSB(OFF_WD0); ld = 2048; K = DFF; mode = CM_P32; t0 = 2048; }
;             else if (it < 2768) { src = p.w_pool; dst = WSB(OFF_WPOOL); ld = 256; K = 256; mode = CM_POOL; t0 = 2752; }
;             else if (it < 2928) { src = p.w_in_c; gain = p.g_mix + 2048; dst = WSB(OFF_WINC); ld = 1088; K = 2048; mode = CM_INC; t0 = 2768; }
;             else if (it < 3024) { src = p.w_uq; gain = p.g_cq; dst = WSB(OFF_WUQ); ld = 3072; K = 512; mode = CM_UQ; t0 = 2928; }
;             else if (it < 3088) { src = p.w_ukv; gain = p.g_ckv; dst = WSB(OFF_WUKK); ld = 4096; K = 512; mode = CM_UKVK; t0 = 3024; }
;             else if (it < 3152) { src = p.w_ukv; gain = p.g_ckv; dst = WSB(OFF_WUKV); ld = 4096; K = 512; mode = CM_UKVV; t0 = 3088; }
;             else if (it < 3408) { src = p.w_out_c; dst = WSB(OFF_WOC); ld = 2048; K = 2048; mode = CM_P32; t0 = 3152; }
;             else if (it < 4816) { src = p.w_gate + (size_t)2048 * DFF; src2 = p.w_up + (size_t)2048 * DFF; gain = p.g_ffn + 2048; dst = WSB(OFF_WGU1); ld = DFF; K = 2048; mode = CM_GU; t0 = 3408; }
;             else { src = p.w_down + (size_t)DFF * 2048; dst = WSB(OFF_WD1); ld = 2048; K = DFF; mode = CM_P32; t0 = 4816; }
;             conv_item(lane, lds + wid * 9216, src, src2, gain, dst, ld, K, mode, coff, it - t0);
.LBB0_898:
	s_and_b64 vcc, exec, s[8:9]
	s_cbranch_vccz .Lconv_skip_2
	s_cmpk_eq_i32 s7, 0x100
	s_cbranch_scc0 .Lconv_skip_2
	s_mov_b32 s12, s6
	s_cmpk_lt_u32 s12, 160
	s_cbranch_scc1 .Lconv_skip_2
	s_mov_b32 s12, s6
	s_addk_i32 s12, -160
	s_mul_i32 s13, s33, 96
	s_add_i32 s12, s12, s13
	s_add_i32 s99, s12, 832
	s_movk_i32 s101, 2367
	s_movk_i32 s100, 768
	s_mov_b32 s98, 4
	s_branch .Lconv_tin
